# XCD barrier: last arriver releases every XCC directly (one hop less), back-to-back polling
# speedup vs baseline: 1.1702x; 1.0044x over previous
; DEVI void grid_barrier(const int TIDX, const int BIDX, const int GDIM, unsigned* bar, unsigned k) {
;   __syncthreads();
;   if (TIDX == 0) {
;     __threadfence();
;     const unsigned g = (unsigned)BIDX & 7u, gs = (unsigned)GDIM >> 3;
;     const unsigned old = __hip_atomic_fetch_add(bar + 32 * (1 + g), 1u, __ATOMIC_RELAXED, __HIP_MEMORY_SCOPE_AGENT);
;     if (old + 1u == gs * k) {
;       __threadfence();
;       __hip_atomic_fetch_add(bar, 1u, __ATOMIC_RELAXED, __HIP_MEMORY_SCOPE_AGENT);
;     }
;     unsigned spins = 0;
;     while (__hip_atomic_load(bar, __ATOMIC_RELAXED, __HIP_MEMORY_SCOPE_AGENT) < 8u * k) {
;       __builtin_amdgcn_s_sleep(1);
;       if (++spins > (1u << 27)) break;
;     }
;     __threadfence();
;   }
;   __syncthreads();
; }
.Lxb_have:
	v_readlane_b32 s6, v255, 3
	s_sub_i32 s9, s12, s6
	v_mov_b32_e32 v1, 1
	global_atomic_add v1, v0, v1, s[2:3] offset:16 sc0
	s_mul_i32 s5, s100, s9
	s_mov_b32 s10, 0x4000
	s_waitcnt vmcnt(0)
	v_readfirstlane_b32 s7, v1
	s_add_i32 s7, s7, 1
	s_cmp_eq_u32 s7, s5
	s_cbranch_scc0 .Lxb_follow
	buffer_wbl2 sc1
	s_waitcnt vmcnt(0)
	v_mov_b32_e32 v1, s100
	v_mov_b32_e32 v2, 0x400
	global_atomic_add v1, v2, v1, s[2:3] sc0
	s_mul_i32 s5, s84, s9
	s_waitcnt vmcnt(0)
	v_readfirstlane_b32 s7, v1
	s_add_i32 s7, s7, s100
	s_cmp_eq_u32 s7, s5
	s_cbranch_scc0 .Lxb_follow
	v_mov_b32_e32 v1, 1
	global_atomic_add v129, v1, s[2:3] offset:32
	global_atomic_add v129, v1, s[2:3] offset:96
	global_atomic_add v129, v1, s[2:3] offset:160
	global_atomic_add v129, v1, s[2:3] offset:224
	global_atomic_add v129, v1, s[2:3] offset:288
	global_atomic_add v129, v1, s[2:3] offset:352
	global_atomic_add v129, v1, s[2:3] offset:416
	global_atomic_add v129, v1, s[2:3] offset:480
	global_atomic_add v129, v1, s[2:3] offset:544
	global_atomic_add v129, v1, s[2:3] offset:608
	global_atomic_add v129, v1, s[2:3] offset:672
	global_atomic_add v129, v1, s[2:3] offset:736
	global_atomic_add v129, v1, s[2:3] offset:800
	global_atomic_add v129, v1, s[2:3] offset:864
	global_atomic_add v129, v1, s[2:3] offset:928
	global_atomic_add v129, v1, s[2:3] offset:992
	buffer_inv sc1
	s_waitcnt vmcnt(0)
	s_branch .LBB0_810
.Lxb_follow:
	global_load_dword v1, v0, s[2:3] offset:32 sc1
	s_waitcnt vmcnt(0)
	v_readfirstlane_b32 s7, v1
	s_cmp_ge_u32 s7, s9
	s_cbranch_scc1 .Lxb_facq
	s_add_i32 s10, s10, -1
	s_cmp_eq_u32 s10, 0
	s_cbranch_scc1 .Lxb_facq
	s_branch .Lxb_follow
